# 7.3 widened stores in P3 V-tile epilogue (ni0/ni1 pairs via v_permlane32_swap -> 8 dwordx4 per lane), all rs ds_reads issued up front
# speedup vs baseline: 1.0017x; 1.0017x over previous
; DI void phase3(const Params& p, char* smem) {
;     ...
;   const int t_begin = bid < 64 ? NQ + NKV : bid - 64, t_step = G - 64;
;   for (int it = t_begin; it < NQ + NKV; it += t_step) {
.LBB0_507:
	v_cvt_pk_bf16_f32 v2, v4, v6
	global_store_dword v[8:9], v2, off offset:4
.Lp3_next:
	s_add_i32 s13, s13, s55
	s_add_i32 s59, s59, s60
	s_add_i32 s64, s64, s65
	v_add_u32_e32 v135, s58, v135
	v_add_u32_e32 v136, s61, v136
	v_add_u32_e32 v137, s63, v137
	s_cmpk_lt_i32 s13, 0x700
	s_cbranch_scc0 .LBB0_535

; template <bool SWAP, class Epi>
; DI void gemm_tile(const u16* __restrict__ A, int lda, const u16* __restrict__ Bt, int ldb, int K, int m0, int n0, char* smem, Epi&& epi) {
;     ...
;   const int srow = tid >> 3, skc = tid & 7;
;   const u16* ag = A + (size_t)(m0 + srow) * lda + skc * 8;
;   const u16* bg = Bt + (size_t)(n0 + srow) * ldb + skc * 8;
;   u16* asw = As + srow * 72 + skc * 8;
;   u16* bsw = Bs + srow * 72 + skc * 8;
;   u32x4 ra0[4], rb0[4], ra1[4], rb1[4];
; #pragma unroll
;   for (int i = 0; i < 4; ++i) { ra0[i] = *(const u32x4*)(ag + (size_t)i * 32 * lda); rb0[i] = *(const u32x4*)(bg + (size_t)i * 32 * ldb); }
; #pragma unroll
;   for (int i = 0; i < 4; ++i) { ra1[i] = *(const u32x4*)(ag + (size_t)i * 32 * lda + 64); rb1[i] = *(const u32x4*)(bg + (size_t)i * 32 * ldb + 64); }
;   __syncthreads();
; #pragma unroll
;   for (int i = 0; i < 4; ++i) { *(u32x4*)(asw + 32 * i * 72) = ra0[i]; *(u32x4*)(bsw + 32 * i * 72) = rb0[i]; }
;   __syncthreads();
;   const int KT = K >> 6;
;   const u16* Asb = As + (wm * 64 + r) * 72 + hi * 8;
;   const u16* Bsb = Bs + (wn * 64 + r) * 72 + hi * 8;
;   auto compute = [&](int buf) __attribute__((always_inline)) {
;     bf16x8 af[2][2], bfr[2][2];
;     af[0][0] = *(const bf16x8*)(Asb + buf * 128 * 72);
;     af[0][1] = *(const bf16x8*)(Asb + buf * 128 * 72 + 32 * 72);
;     bfr[0][0] = *(const bf16x8*)(Bsb + buf * 128 * 72);
;     bfr[0][1] = *(const bf16x8*)(Bsb + buf * 128 * 72 + 32 * 72);
; #pragma unroll
;     for (int ks = 0; ks < 4; ++ks) {
;       const int c = ks & 1, n = c ^ 1;
;       if (ks < 3) {
;         af[n][0] = *(const bf16x8*)(Asb + buf * 128 * 72 + (ks + 1) * 16);
;         af[n][1] = *(const bf16x8*)(Asb + buf * 128 * 72 + 32 * 72 + (ks + 1) * 16);
;         bfr[n][0] = *(const bf16x8*)(Bsb + buf * 128 * 72 + (ks + 1) * 16);
;         bfr[n][1] = *(const bf16x8*)(Bsb + buf * 128 * 72 + 32 * 72 + (ks + 1) * 16);
;       }
;       __builtin_amdgcn_sched_barrier(0);
; #pragma unroll
;       for (int mi = 0; mi < 2; ++mi)
; #pragma unroll
;         for (int ni = 0; ni < 2; ++ni) {
;           if (SWAP) acc[mi][ni] = MFMA(bfr[c][ni], af[c][mi], acc[mi][ni]);
;           else acc[mi][ni] = MFMA(af[c][mi], bfr[c][ni], acc[mi][ni]);
;         }
;       __builtin_amdgcn_sched_barrier(0);
;     }
;   };
;   for (int kt = 0; kt < KT; kt += 2) {
;     if (kt + 2 < KT) {
;       const int k0 = (kt + 2) << 6;
.LBB0_511:
	s_or_b64 exec, exec, s[50:51]
	s_lshl_b32 s92, s92, 7
	s_and_b32 s51, s64, 0x7fff0000
	v_or_b32_e32 v2, s92, v120
	v_mul_u32_u24_e32 v66, 0x2080, v2
	v_or_b32_e32 v2, s51, v134
	s_add_i32 s16, s13, 0xfffffd00
	v_lshl_add_u64 v[80:81], v[68:69], 0, v[66:67]
	v_lshlrev_b32_e32 v66, 1, v2
	s_lshr_b32 s16, s16, 7
	s_and_b32 s50, s13, 64
	v_lshl_add_u64 v[82:83], v[74:75], 0, v[66:67]
	s_cmp_lg_u32 s50, 0
	v_lshl_add_u64 v[90:91], v[80:81], 0, s[18:19]
	v_lshl_add_u64 v[88:89], v[80:81], 0, s[20:21]
	v_lshl_add_u64 v[86:87], v[80:81], 0, s[22:23]
	v_lshl_add_u64 v[84:85], v[80:81], 0, s[24:25]
	v_lshl_add_u64 v[106:107], v[82:83], 0, s[26:27]
	v_lshl_add_u64 v[104:105], v[82:83], 0, s[28:29]
	v_lshl_add_u64 v[102:103], v[82:83], 0, s[30:31]
	v_lshl_add_u64 v[92:93], v[82:83], 0, s[34:35]
	v_lshl_add_u64 v[94:95], v[80:81], 0, s[36:37]
	v_lshl_add_u64 v[96:97], v[82:83], 0, s[42:43]
	v_lshl_add_u64 v[98:99], v[80:81], 0, s[44:45]
	v_lshl_add_u64 v[100:101], v[82:83], 0, s[46:47]
	s_mov_b64 s[50:51], -1
	s_cbranch_scc0 .LBB0_513
	global_load_dwordx4 v[2:5], v[80:81], off
	global_load_dwordx4 v[6:9], v[82:83], off
	global_load_dwordx4 v[10:13], v[90:91], off
	global_load_dwordx4 v[14:17], v[106:107], off
	global_load_dwordx4 v[18:21], v[88:89], off
	global_load_dwordx4 v[22:25], v[104:105], off
	global_load_dwordx4 v[26:29], v[86:87], off
	global_load_dwordx4 v[30:33], v[102:103], off
	global_load_dwordx4 v[140:143], v[80:81], off offset:128
	global_load_dwordx4 v[144:147], v[82:83], off offset:128
	global_load_dwordx4 v[148:151], v[84:85], off
	global_load_dwordx4 v[152:155], v[92:93], off
	global_load_dwordx4 v[156:159], v[94:95], off
	global_load_dwordx4 v[160:163], v[96:97], off
	global_load_dwordx4 v[164:167], v[98:99], off
	global_load_dwordx4 v[168:171], v[100:101], off
	v_add_co_u32_e32 v108, vcc, s67, v80
	s_waitcnt lgkmcnt(0)
	s_nop 0
	v_addc_co_u32_e32 v109, vcc, 0, v81, vcc
	v_add_co_u32_e32 v110, vcc, s70, v82
	s_barrier
	s_nop 0
	v_addc_co_u32_e32 v111, vcc, 0, v83, vcc
	v_add_co_u32_e32 v112, vcc, s71, v80
	s_nop 1
	v_addc_co_u32_e32 v113, vcc, 0, v81, vcc
	s_waitcnt vmcnt(16)
	v_add_co_u32_e32 v114, vcc, s72, v82
	s_waitcnt vmcnt(15)
	ds_write_b128 v121, v[2:5] offset:16
	s_waitcnt vmcnt(14)
	ds_write_b128 v121, v[6:9] offset:36880
	s_waitcnt vmcnt(13)
	ds_write_b128 v121, v[10:13] offset:4624
	s_waitcnt vmcnt(12)
	ds_write_b128 v121, v[14:17] offset:41488
	s_waitcnt vmcnt(11)
	ds_write_b128 v121, v[18:21] offset:9232
	s_waitcnt vmcnt(10)
	ds_write_b128 v121, v[22:25] offset:46096
	s_waitcnt vmcnt(9)
	ds_write_b128 v121, v[26:29] offset:13840
	s_waitcnt vmcnt(8)
	ds_write_b128 v121, v[30:33] offset:50704
	v_addc_co_u32_e32 v115, vcc, 0, v83, vcc
	v_add_co_u32_e32 v116, vcc, s73, v80
	s_waitcnt lgkmcnt(0)
	s_nop 0
	v_addc_co_u32_e32 v117, vcc, 0, v81, vcc
	v_add_co_u32_e32 v118, vcc, s62, v82
	s_barrier
	s_nop 0
	v_addc_co_u32_e32 v119, vcc, 0, v83, vcc
	global_load_dwordx4 v[172:175], v[80:81], off offset:256
	global_load_dwordx4 v[176:179], v[82:83], off offset:256
	global_load_dwordx4 v[180:183], v[108:109], off offset:256
	global_load_dwordx4 v[184:187], v[110:111], off offset:256
	global_load_dwordx4 v[190:193], v[112:113], off offset:256
	global_load_dwordx4 v[194:197], v[114:115], off offset:256
	global_load_dwordx4 v[198:201], v[116:117], off offset:256
	global_load_dwordx4 v[202:205], v[118:119], off offset:256
	ds_read_b128 v[2:5], v124 offset:16
	ds_read_b128 v[206:209], v124 offset:48
	ds_read_b128 v[6:9], v124 offset:4624
	ds_read_b128 v[210:213], v124 offset:4656
	ds_read_b128 v[10:13], v126 offset:36880
	ds_read_b128 v[214:217], v126 offset:36912
	ds_read_b128 v[14:17], v126 offset:41488
	ds_read_b128 v[218:221], v126 offset:41520
	s_waitcnt lgkmcnt(3)
	v_mfma_f32_32x32x16_bf16 v[50:65], v[2:5], v[10:13], 0
	s_waitcnt lgkmcnt(1)
	v_mfma_f32_32x32x16_bf16 v[34:49], v[2:5], v[14:17], 0
	v_mfma_f32_32x32x16_bf16 v[18:33], v[6:9], v[10:13], 0
	v_mfma_f32_32x32x16_bf16 v[2:17], v[6:9], v[14:17], 0
	ds_read_b128 v[222:225], v124 offset:80
	ds_read_b128 v[226:229], v124 offset:4688
	ds_read_b128 v[230:233], v126 offset:36944
	ds_read_b128 v[234:237], v126 offset:41552
	s_waitcnt lgkmcnt(4)
	v_mfma_f32_32x32x16_bf16 v[2:17], v[210:213], v[218:221], v[2:17]
	v_mfma_f32_32x32x16_bf16 v[50:65], v[206:209], v[214:217], v[50:65]
	v_mfma_f32_32x32x16_bf16 v[34:49], v[206:209], v[218:221], v[34:49]
	v_mfma_f32_32x32x16_bf16 v[18:33], v[210:213], v[214:217], v[18:33]
	ds_read_b128 v[206:209], v124 offset:112
	ds_read_b128 v[210:213], v124 offset:4720
	ds_read_b128 v[214:217], v126 offset:36976
	ds_read_b128 v[218:221], v126 offset:41584
	s_waitcnt lgkmcnt(4)
	v_mfma_f32_32x32x16_bf16 v[2:17], v[226:229], v[234:237], v[2:17]
	v_mfma_f32_32x32x16_bf16 v[50:65], v[222:225], v[230:233], v[50:65]
	v_mfma_f32_32x32x16_bf16 v[34:49], v[222:225], v[234:237], v[34:49]
	v_mfma_f32_32x32x16_bf16 v[18:33], v[226:229], v[230:233], v[18:33]
	s_waitcnt lgkmcnt(0)
	v_mfma_f32_32x32x16_bf16 v[2:17], v[210:213], v[218:221], v[2:17]
	v_mfma_f32_32x32x16_bf16 v[50:65], v[206:209], v[214:217], v[50:65]
	v_mfma_f32_32x32x16_bf16 v[34:49], v[206:209], v[218:221], v[34:49]
	v_mfma_f32_32x32x16_bf16 v[18:33], v[210:213], v[214:217], v[18:33]
	s_waitcnt vmcnt(15)
	ds_write_b128 v121, v[140:143] offset:18448
	s_waitcnt vmcnt(14)
	ds_write_b128 v121, v[144:147] offset:55312
	s_waitcnt vmcnt(13)
	ds_write_b128 v121, v[148:151] offset:23056
	s_waitcnt vmcnt(12)
	ds_write_b128 v121, v[152:155] offset:59920
	s_waitcnt vmcnt(11)
	ds_write_b128 v121, v[156:159] offset:27664
	s_waitcnt vmcnt(10)
	ds_write_b128 v121, v[160:163] offset:64528
	s_waitcnt vmcnt(9)
	ds_write_b128 v121, v[164:167] offset:32272
	s_waitcnt vmcnt(8)
	ds_write_b128 v122, v[168:171] offset:32256
	s_waitcnt lgkmcnt(0)
	s_barrier
; template <bool SWAP, class Epi>
; DI void gemm_tile(const u16* __restrict__ A, int lda, const u16* __restrict__ Bt, int ldb, int K, int m0, int n0, char* smem, Epi&& epi) {
;     ...
;   for (int kt = 0; kt < KT; kt += 2) {
;     if (kt + 2 < KT) {
;       const int k0 = (kt + 2) << 6;
; #pragma unroll
;       for (int i = 0; i < 4; ++i) { ra0[i] = *(const u32x4*)(ag + (size_t)i * 32 * lda + k0); rb0[i] = *(const u32x4*)(bg + (size_t)i * 32 * ldb + k0); }
;     }
;     compute(0);
; #pragma unroll
;     for (int i = 0; i < 4; ++i) { *(u32x4*)(asw + 128 * 72 + 32 * i * 72) = ra1[i]; *(u32x4*)(bsw + 128 * 72 + 32 * i * 72) = rb1[i]; }
;     __syncthreads();
;     if (kt + 3 < KT) {
;       const int k0 = (kt + 3) << 6;
; #pragma unroll
;       for (int i = 0; i < 4; ++i) { ra1[i] = *(const u32x4*)(ag + (size_t)i * 32 * lda + k0); rb1[i] = *(const u32x4*)(bg + (size_t)i * 32 * ldb + k0); }
;     }
;     compute(1);
;     if (kt + 2 < KT) {
; #pragma unroll
;       for (int i = 0; i < 4; ++i) { *(u32x4*)(asw + 32 * i * 72) = ra0[i]; *(u32x4*)(bsw + 32 * i * 72) = rb0[i]; }
;     }
;     __syncthreads();
	global_load_dwordx4 v[140:143], v[80:81], off offset:384
	global_load_dwordx4 v[144:147], v[82:83], off offset:384
	global_load_dwordx4 v[148:151], v[108:109], off offset:384
	global_load_dwordx4 v[152:155], v[110:111], off offset:384
	global_load_dwordx4 v[156:159], v[112:113], off offset:384
	global_load_dwordx4 v[160:163], v[114:115], off offset:384
	global_load_dwordx4 v[164:167], v[116:117], off offset:384
	global_load_dwordx4 v[168:171], v[118:119], off offset:384
	ds_read_b128 v[206:209], v124 offset:18448
	ds_read_b128 v[210:213], v124 offset:18480
	ds_read_b128 v[214:217], v124 offset:23056
	ds_read_b128 v[218:221], v124 offset:23088
	ds_read_b128 v[222:225], v126 offset:55312
	ds_read_b128 v[226:229], v126 offset:55344
	ds_read_b128 v[230:233], v126 offset:59920
	ds_read_b128 v[234:237], v126 offset:59952
	s_waitcnt lgkmcnt(1)
	v_mfma_f32_32x32x16_bf16 v[2:17], v[214:217], v[230:233], v[2:17]
	v_mfma_f32_32x32x16_bf16 v[50:65], v[206:209], v[222:225], v[50:65]
	v_mfma_f32_32x32x16_bf16 v[34:49], v[206:209], v[230:233], v[34:49]
	v_mfma_f32_32x32x16_bf16 v[18:33], v[214:217], v[222:225], v[18:33]
	ds_read_b128 v[206:209], v124 offset:18512
	ds_read_b128 v[214:217], v124 offset:23120
	ds_read_b128 v[222:225], v126 offset:55376
	ds_read_b128 v[230:233], v126 offset:59984
	s_waitcnt lgkmcnt(4)
	v_mfma_f32_32x32x16_bf16 v[2:17], v[218:221], v[234:237], v[2:17]
	v_mfma_f32_32x32x16_bf16 v[50:65], v[210:213], v[226:229], v[50:65]
	v_mfma_f32_32x32x16_bf16 v[34:49], v[210:213], v[234:237], v[34:49]
	v_mfma_f32_32x32x16_bf16 v[18:33], v[218:221], v[226:229], v[18:33]
	ds_read_b128 v[210:213], v124 offset:18544
	ds_read_b128 v[218:221], v124 offset:23152
	ds_read_b128 v[226:229], v126 offset:55408
	ds_read_b128 v[234:237], v126 offset:60016
	s_waitcnt lgkmcnt(4)
	v_mfma_f32_32x32x16_bf16 v[2:17], v[214:217], v[230:233], v[2:17]
	v_mfma_f32_32x32x16_bf16 v[50:65], v[206:209], v[222:225], v[50:65]
	v_mfma_f32_32x32x16_bf16 v[34:49], v[206:209], v[230:233], v[34:49]
	v_mfma_f32_32x32x16_bf16 v[18:33], v[214:217], v[222:225], v[18:33]
	s_waitcnt lgkmcnt(0)
	v_mfma_f32_32x32x16_bf16 v[2:17], v[218:221], v[234:237], v[2:17]
	v_mfma_f32_32x32x16_bf16 v[50:65], v[210:213], v[226:229], v[50:65]
	v_mfma_f32_32x32x16_bf16 v[34:49], v[210:213], v[234:237], v[34:49]
	v_mfma_f32_32x32x16_bf16 v[18:33], v[218:221], v[226:229], v[18:33]
	s_waitcnt vmcnt(15)
	ds_write_b128 v121, v[172:175] offset:16
	s_waitcnt vmcnt(14)
	ds_write_b128 v121, v[176:179] offset:36880
	s_waitcnt vmcnt(13)
	ds_write_b128 v121, v[180:183] offset:4624
	s_waitcnt vmcnt(12)
	ds_write_b128 v121, v[184:187] offset:41488
	s_waitcnt vmcnt(11)
	ds_write_b128 v121, v[190:193] offset:9232
	s_waitcnt vmcnt(10)
	ds_write_b128 v121, v[194:197] offset:46096
	s_waitcnt vmcnt(9)
	ds_write_b128 v121, v[198:201] offset:13840
	s_waitcnt vmcnt(8)
	ds_write_b128 v121, v[202:205] offset:50704
	s_waitcnt lgkmcnt(0)
	s_barrier
	global_load_dwordx4 v[172:175], v[80:81], off offset:512
	global_load_dwordx4 v[176:179], v[82:83], off offset:512
	global_load_dwordx4 v[180:183], v[108:109], off offset:512
	global_load_dwordx4 v[184:187], v[110:111], off offset:512
	global_load_dwordx4 v[190:193], v[112:113], off offset:512
	global_load_dwordx4 v[194:197], v[114:115], off offset:512
	global_load_dwordx4 v[198:201], v[116:117], off offset:512
	global_load_dwordx4 v[202:205], v[118:119], off offset:512
	ds_read_b128 v[206:209], v124 offset:16
	ds_read_b128 v[210:213], v124 offset:48
	ds_read_b128 v[214:217], v124 offset:4624
	ds_read_b128 v[218:221], v124 offset:4656
	ds_read_b128 v[222:225], v126 offset:36880
	ds_read_b128 v[226:229], v126 offset:36912
	ds_read_b128 v[230:233], v126 offset:41488
	ds_read_b128 v[234:237], v126 offset:41520
	s_waitcnt lgkmcnt(1)
	v_mfma_f32_32x32x16_bf16 v[2:17], v[214:217], v[230:233], v[2:17]
	v_mfma_f32_32x32x16_bf16 v[50:65], v[206:209], v[222:225], v[50:65]
	v_mfma_f32_32x32x16_bf16 v[34:49], v[206:209], v[230:233], v[34:49]
	v_mfma_f32_32x32x16_bf16 v[18:33], v[214:217], v[222:225], v[18:33]
	ds_read_b128 v[206:209], v124 offset:80
	ds_read_b128 v[214:217], v124 offset:4688
	ds_read_b128 v[222:225], v126 offset:36944
	ds_read_b128 v[230:233], v126 offset:41552
	s_waitcnt lgkmcnt(4)
	v_mfma_f32_32x32x16_bf16 v[2:17], v[218:221], v[234:237], v[2:17]
	v_mfma_f32_32x32x16_bf16 v[50:65], v[210:213], v[226:229], v[50:65]
	v_mfma_f32_32x32x16_bf16 v[34:49], v[210:213], v[234:237], v[34:49]
	v_mfma_f32_32x32x16_bf16 v[18:33], v[218:221], v[226:229], v[18:33]
	ds_read_b128 v[210:213], v124 offset:112
	ds_read_b128 v[218:221], v124 offset:4720
	ds_read_b128 v[226:229], v126 offset:36976
	ds_read_b128 v[234:237], v126 offset:41584
	s_waitcnt lgkmcnt(4)
	v_mfma_f32_32x32x16_bf16 v[2:17], v[214:217], v[230:233], v[2:17]
	v_mfma_f32_32x32x16_bf16 v[50:65], v[206:209], v[222:225], v[50:65]
	v_mfma_f32_32x32x16_bf16 v[34:49], v[206:209], v[230:233], v[34:49]
	v_mfma_f32_32x32x16_bf16 v[18:33], v[214:217], v[222:225], v[18:33]
	s_waitcnt lgkmcnt(0)
	v_mfma_f32_32x32x16_bf16 v[2:17], v[218:221], v[234:237], v[2:17]
	v_mfma_f32_32x32x16_bf16 v[50:65], v[210:213], v[226:229], v[50:65]
	v_mfma_f32_32x32x16_bf16 v[34:49], v[210:213], v[234:237], v[34:49]
	v_mfma_f32_32x32x16_bf16 v[18:33], v[218:221], v[226:229], v[18:33]
	s_waitcnt vmcnt(15)
	ds_write_b128 v121, v[140:143] offset:18448
	s_waitcnt vmcnt(14)
	ds_write_b128 v121, v[144:147] offset:55312
	s_waitcnt vmcnt(13)
	ds_write_b128 v121, v[148:151] offset:23056
	s_waitcnt vmcnt(12)
	ds_write_b128 v121, v[152:155] offset:59920
	s_waitcnt vmcnt(11)
	ds_write_b128 v121, v[156:159] offset:27664
	s_waitcnt vmcnt(10)
	ds_write_b128 v121, v[160:163] offset:64528
	s_waitcnt vmcnt(9)
	ds_write_b128 v121, v[164:167] offset:32272
	s_waitcnt vmcnt(8)
	ds_write_b128 v122, v[168:171] offset:32256
	s_waitcnt lgkmcnt(0)
	s_barrier
; template <bool SWAP, class Epi>
; DI void gemm_tile(const u16* __restrict__ A, int lda, const u16* __restrict__ Bt, int ldb, int K, int m0, int n0, char* smem, Epi&& epi) {
;     ...
;   for (int kt = 0; kt < KT; kt += 2) {
;     if (kt + 2 < KT) {
;       const int k0 = (kt + 2) << 6;
; #pragma unroll
;       for (int i = 0; i < 4; ++i) { ra0[i] = *(const u32x4*)(ag + (size_t)i * 32 * lda + k0); rb0[i] = *(const u32x4*)(bg + (size_t)i * 32 * ldb + k0); }
;     }
;     compute(0);
; #pragma unroll
;     for (int i = 0; i < 4; ++i) { *(u32x4*)(asw + 128 * 72 + 32 * i * 72) = ra1[i]; *(u32x4*)(bsw + 128 * 72 + 32 * i * 72) = rb1[i]; }
;     __syncthreads();
;     if (kt + 3 < KT) {
;       const int k0 = (kt + 3) << 6;
; #pragma unroll
;       for (int i = 0; i < 4; ++i) { ra1[i] = *(const u32x4*)(ag + (size_t)i * 32 * lda + k0); rb1[i] = *(const u32x4*)(bg + (size_t)i * 32 * ldb + k0); }
;     }
;     compute(1);
;     if (kt + 2 < KT) {
; #pragma unroll
;       for (int i = 0; i < 4; ++i) { *(u32x4*)(asw + 32 * i * 72) = ra0[i]; *(u32x4*)(bsw + 32 * i * 72) = rb0[i]; }
;     }
;     __syncthreads();
	global_load_dwordx4 v[140:143], v[80:81], off offset:640
	global_load_dwordx4 v[144:147], v[82:83], off offset:640
	global_load_dwordx4 v[148:151], v[108:109], off offset:640
	global_load_dwordx4 v[152:155], v[110:111], off offset:640
	global_load_dwordx4 v[156:159], v[112:113], off offset:640
	global_load_dwordx4 v[160:163], v[114:115], off offset:640
	global_load_dwordx4 v[164:167], v[116:117], off offset:640
	global_load_dwordx4 v[168:171], v[118:119], off offset:640
	ds_read_b128 v[206:209], v124 offset:18448
	ds_read_b128 v[210:213], v124 offset:18480
	ds_read_b128 v[214:217], v124 offset:23056
	ds_read_b128 v[218:221], v124 offset:23088
	ds_read_b128 v[222:225], v126 offset:55312
	ds_read_b128 v[226:229], v126 offset:55344
	ds_read_b128 v[230:233], v126 offset:59920
	ds_read_b128 v[234:237], v126 offset:59952
	s_waitcnt lgkmcnt(1)
	v_mfma_f32_32x32x16_bf16 v[2:17], v[214:217], v[230:233], v[2:17]
	v_mfma_f32_32x32x16_bf16 v[50:65], v[206:209], v[222:225], v[50:65]
	v_mfma_f32_32x32x16_bf16 v[34:49], v[206:209], v[230:233], v[34:49]
	v_mfma_f32_32x32x16_bf16 v[18:33], v[214:217], v[222:225], v[18:33]
	ds_read_b128 v[206:209], v124 offset:18512
	ds_read_b128 v[214:217], v124 offset:23120
	ds_read_b128 v[222:225], v126 offset:55376
	ds_read_b128 v[230:233], v126 offset:59984
	s_waitcnt lgkmcnt(4)
	v_mfma_f32_32x32x16_bf16 v[2:17], v[218:221], v[234:237], v[2:17]
	v_mfma_f32_32x32x16_bf16 v[50:65], v[210:213], v[226:229], v[50:65]
	v_mfma_f32_32x32x16_bf16 v[34:49], v[210:213], v[234:237], v[34:49]
	v_mfma_f32_32x32x16_bf16 v[18:33], v[218:221], v[226:229], v[18:33]
	ds_read_b128 v[210:213], v124 offset:18544
	ds_read_b128 v[218:221], v124 offset:23152
	ds_read_b128 v[226:229], v126 offset:55408
	ds_read_b128 v[234:237], v126 offset:60016
	s_waitcnt lgkmcnt(4)
	v_mfma_f32_32x32x16_bf16 v[2:17], v[214:217], v[230:233], v[2:17]
	v_mfma_f32_32x32x16_bf16 v[50:65], v[206:209], v[222:225], v[50:65]
	v_mfma_f32_32x32x16_bf16 v[34:49], v[206:209], v[230:233], v[34:49]
	v_mfma_f32_32x32x16_bf16 v[18:33], v[214:217], v[222:225], v[18:33]
	s_waitcnt lgkmcnt(0)
	v_mfma_f32_32x32x16_bf16 v[2:17], v[218:221], v[234:237], v[2:17]
	v_mfma_f32_32x32x16_bf16 v[50:65], v[210:213], v[226:229], v[50:65]
	v_mfma_f32_32x32x16_bf16 v[34:49], v[210:213], v[234:237], v[34:49]
	v_mfma_f32_32x32x16_bf16 v[18:33], v[218:221], v[226:229], v[18:33]
	s_waitcnt vmcnt(15)
	ds_write_b128 v121, v[172:175] offset:16
	s_waitcnt vmcnt(14)
	ds_write_b128 v121, v[176:179] offset:36880
	s_waitcnt vmcnt(13)
	ds_write_b128 v121, v[180:183] offset:4624
	s_waitcnt vmcnt(12)
	ds_write_b128 v121, v[184:187] offset:41488
	s_waitcnt vmcnt(11)
	ds_write_b128 v121, v[190:193] offset:9232
	s_waitcnt vmcnt(10)
	ds_write_b128 v121, v[194:197] offset:46096
	s_waitcnt vmcnt(9)
	ds_write_b128 v121, v[198:201] offset:13840
	s_waitcnt vmcnt(8)
	ds_write_b128 v121, v[202:205] offset:50704
	s_waitcnt lgkmcnt(0)
	s_barrier
	global_load_dwordx4 v[172:175], v[80:81], off offset:768
	global_load_dwordx4 v[176:179], v[82:83], off offset:768
	global_load_dwordx4 v[180:183], v[108:109], off offset:768
	global_load_dwordx4 v[184:187], v[110:111], off offset:768
	global_load_dwordx4 v[190:193], v[112:113], off offset:768
	global_load_dwordx4 v[194:197], v[114:115], off offset:768
	global_load_dwordx4 v[198:201], v[116:117], off offset:768
	global_load_dwordx4 v[202:205], v[118:119], off offset:768
	ds_read_b128 v[206:209], v124 offset:16
	ds_read_b128 v[210:213], v124 offset:48
	ds_read_b128 v[214:217], v124 offset:4624
	ds_read_b128 v[218:221], v124 offset:4656
	ds_read_b128 v[222:225], v126 offset:36880
	ds_read_b128 v[226:229], v126 offset:36912
	ds_read_b128 v[230:233], v126 offset:41488
	ds_read_b128 v[234:237], v126 offset:41520
	s_waitcnt lgkmcnt(1)
	v_mfma_f32_32x32x16_bf16 v[2:17], v[214:217], v[230:233], v[2:17]
	v_mfma_f32_32x32x16_bf16 v[50:65], v[206:209], v[222:225], v[50:65]
	v_mfma_f32_32x32x16_bf16 v[34:49], v[206:209], v[230:233], v[34:49]
	v_mfma_f32_32x32x16_bf16 v[18:33], v[214:217], v[222:225], v[18:33]
	ds_read_b128 v[206:209], v124 offset:80
	ds_read_b128 v[214:217], v124 offset:4688
	ds_read_b128 v[222:225], v126 offset:36944
	ds_read_b128 v[230:233], v126 offset:41552
	s_waitcnt lgkmcnt(4)
	v_mfma_f32_32x32x16_bf16 v[2:17], v[218:221], v[234:237], v[2:17]
	v_mfma_f32_32x32x16_bf16 v[50:65], v[210:213], v[226:229], v[50:65]
	v_mfma_f32_32x32x16_bf16 v[34:49], v[210:213], v[234:237], v[34:49]
	v_mfma_f32_32x32x16_bf16 v[18:33], v[218:221], v[226:229], v[18:33]
	ds_read_b128 v[210:213], v124 offset:112
	ds_read_b128 v[218:221], v124 offset:4720
	ds_read_b128 v[226:229], v126 offset:36976
	ds_read_b128 v[234:237], v126 offset:41584
	s_waitcnt lgkmcnt(4)
	v_mfma_f32_32x32x16_bf16 v[2:17], v[214:217], v[230:233], v[2:17]
	v_mfma_f32_32x32x16_bf16 v[50:65], v[206:209], v[222:225], v[50:65]
	v_mfma_f32_32x32x16_bf16 v[34:49], v[206:209], v[230:233], v[34:49]
	v_mfma_f32_32x32x16_bf16 v[18:33], v[214:217], v[222:225], v[18:33]
	s_waitcnt lgkmcnt(0)
	v_mfma_f32_32x32x16_bf16 v[2:17], v[218:221], v[234:237], v[2:17]
	v_mfma_f32_32x32x16_bf16 v[50:65], v[210:213], v[226:229], v[50:65]
	v_mfma_f32_32x32x16_bf16 v[34:49], v[210:213], v[234:237], v[34:49]
	v_mfma_f32_32x32x16_bf16 v[18:33], v[218:221], v[226:229], v[18:33]
	s_waitcnt vmcnt(15)
	ds_write_b128 v121, v[140:143] offset:18448
	s_waitcnt vmcnt(14)
	ds_write_b128 v121, v[144:147] offset:55312
	s_waitcnt vmcnt(13)
	ds_write_b128 v121, v[148:151] offset:23056
	s_waitcnt vmcnt(12)
	ds_write_b128 v121, v[152:155] offset:59920
	s_waitcnt vmcnt(11)
	ds_write_b128 v121, v[156:159] offset:27664
	s_waitcnt vmcnt(10)
	ds_write_b128 v121, v[160:163] offset:64528
	s_waitcnt vmcnt(9)
	ds_write_b128 v121, v[164:167] offset:32272
	s_waitcnt vmcnt(8)
	ds_write_b128 v122, v[168:171] offset:32256
	s_waitcnt lgkmcnt(0)
	s_barrier
; #define MFMA(a, b, c) __builtin_amdgcn_mfma_f32_32x32x16_bf16((a), (b), (c), 0, 0, 0)
; template <bool SWAP, class Epi>
; DI void gemm_tile(const u16* __restrict__ A, int lda, const u16* __restrict__ Bt, int ldb, int K, int m0, int n0, char* smem, Epi&& epi) {
;     ...
;   auto compute = [&](int buf) __attribute__((always_inline)) {
;     bf16x8 af[2][2], bfr[2][2];
;     af[0][0] = *(const bf16x8*)(Asb + buf * 128 * 72);
;     af[0][1] = *(const bf16x8*)(Asb + buf * 128 * 72 + 32 * 72);
;     bfr[0][0] = *(const bf16x8*)(Bsb + buf * 128 * 72);
;     bfr[0][1] = *(const bf16x8*)(Bsb + buf * 128 * 72 + 32 * 72);
; #pragma unroll
;     for (int ks = 0; ks < 4; ++ks) {
;       const int c = ks & 1, n = c ^ 1;
;       if (ks < 3) {
;         af[n][0] = *(const bf16x8*)(Asb + buf * 128 * 72 + (ks + 1) * 16);
;         af[n][1] = *(const bf16x8*)(Asb + buf * 128 * 72 + 32 * 72 + (ks + 1) * 16);
;         bfr[n][0] = *(const bf16x8*)(Bsb + buf * 128 * 72 + (ks + 1) * 16);
;         bfr[n][1] = *(const bf16x8*)(Bsb + buf * 128 * 72 + 32 * 72 + (ks + 1) * 16);
;       }
;       __builtin_amdgcn_sched_barrier(0);
; #pragma unroll
;       for (int mi = 0; mi < 2; ++mi)
; #pragma unroll
;         for (int ni = 0; ni < 2; ++ni) {
;           if (SWAP) acc[mi][ni] = MFMA(bfr[c][ni], af[c][mi], acc[mi][ni]);
;           else acc[mi][ni] = MFMA(af[c][mi], bfr[c][ni], acc[mi][ni]);
;         }
;       __builtin_amdgcn_sched_barrier(0);
;     }
;   };
;   for (int kt = 0; kt < KT; kt += 2) {
;     if (kt + 2 < KT) {
;       const int k0 = (kt + 2) << 6;
; #pragma unroll
;       for (int i = 0; i < 4; ++i) { ra0[i] = *(const u32x4*)(ag + (size_t)i * 32 * lda + k0); rb0[i] = *(const u32x4*)(bg + (size_t)i * 32 * ldb + k0); }
;     }
;     compute(0);
; #pragma unroll
;     for (int i = 0; i < 4; ++i) { *(u32x4*)(asw + 128 * 72 + 32 * i * 72) = ra1[i]; *(u32x4*)(bsw + 128 * 72 + 32 * i * 72) = rb1[i]; }
;     __syncthreads();
;     if (kt + 3 < KT) {
;       const int k0 = (kt + 3) << 6;
; #pragma unroll
;       for (int i = 0; i < 4; ++i) { ra1[i] = *(const u32x4*)(ag + (size_t)i * 32 * lda + k0); rb1[i] = *(const u32x4*)(bg + (size_t)i * 32 * ldb + k0); }
;     }
;     compute(1);
;     if (kt + 2 < KT) {
; #pragma unroll
;       for (int i = 0; i < 4; ++i) { *(u32x4*)(asw + 32 * i * 72) = ra0[i]; *(u32x4*)(bsw + 32 * i * 72) = rb0[i]; }
;     }
;     __syncthreads();
	global_load_dwordx4 v[140:143], v[80:81], off offset:896
	global_load_dwordx4 v[144:147], v[82:83], off offset:896
	global_load_dwordx4 v[148:151], v[108:109], off offset:896
	s_nop 0
	global_load_dwordx4 v[108:111], v[110:111], off offset:896
	s_nop 0
	global_load_dwordx4 v[152:155], v[112:113], off offset:896
	s_nop 0
	global_load_dwordx4 v[112:115], v[114:115], off offset:896
	s_nop 0
	global_load_dwordx4 v[156:159], v[116:117], off offset:896
	s_nop 0
	global_load_dwordx4 v[116:119], v[118:119], off offset:896
	ds_read_b128 v[160:163], v124 offset:18448
	ds_read_b128 v[164:167], v124 offset:18480
	ds_read_b128 v[168:171], v124 offset:23056
	ds_read_b128 v[206:209], v124 offset:23088
	ds_read_b128 v[210:213], v126 offset:55312
	ds_read_b128 v[214:217], v126 offset:55344
	ds_read_b128 v[218:221], v126 offset:59920
	ds_read_b128 v[222:225], v126 offset:59952
	s_waitcnt lgkmcnt(1)
	v_mfma_f32_32x32x16_bf16 v[2:17], v[168:171], v[218:221], v[2:17]
	v_mfma_f32_32x32x16_bf16 v[50:65], v[160:163], v[210:213], v[50:65]
	v_mfma_f32_32x32x16_bf16 v[34:49], v[160:163], v[218:221], v[34:49]
	v_mfma_f32_32x32x16_bf16 v[18:33], v[168:171], v[210:213], v[18:33]
	ds_read_b128 v[160:163], v124 offset:18512
	ds_read_b128 v[168:171], v124 offset:23120
	ds_read_b128 v[210:213], v126 offset:55376
	ds_read_b128 v[218:221], v126 offset:59984
	s_waitcnt lgkmcnt(4)
	v_mfma_f32_32x32x16_bf16 v[2:17], v[206:209], v[222:225], v[2:17]
	v_mfma_f32_32x32x16_bf16 v[50:65], v[164:167], v[214:217], v[50:65]
	v_mfma_f32_32x32x16_bf16 v[34:49], v[164:167], v[222:225], v[34:49]
	v_mfma_f32_32x32x16_bf16 v[18:33], v[206:209], v[214:217], v[18:33]
	ds_read_b128 v[164:167], v124 offset:18544
	ds_read_b128 v[206:209], v124 offset:23152
	ds_read_b128 v[214:217], v126 offset:55408
	ds_read_b128 v[222:225], v126 offset:60016
	s_waitcnt lgkmcnt(4)
	v_mfma_f32_32x32x16_bf16 v[2:17], v[168:171], v[218:221], v[2:17]
	v_mfma_f32_32x32x16_bf16 v[50:65], v[160:163], v[210:213], v[50:65]
	v_mfma_f32_32x32x16_bf16 v[34:49], v[160:163], v[218:221], v[34:49]
	v_mfma_f32_32x32x16_bf16 v[18:33], v[168:171], v[210:213], v[18:33]
	s_waitcnt lgkmcnt(0)
	v_mfma_f32_32x32x16_bf16 v[2:17], v[206:209], v[222:225], v[2:17]
	v_mfma_f32_32x32x16_bf16 v[50:65], v[164:167], v[214:217], v[50:65]
	v_mfma_f32_32x32x16_bf16 v[34:49], v[164:167], v[222:225], v[34:49]
	v_mfma_f32_32x32x16_bf16 v[18:33], v[206:209], v[214:217], v[18:33]
	s_waitcnt vmcnt(15)
	ds_write_b128 v121, v[172:175] offset:16
	s_waitcnt vmcnt(14)
	ds_write_b128 v121, v[176:179] offset:36880
	s_waitcnt vmcnt(13)
	ds_write_b128 v121, v[180:183] offset:4624
	s_waitcnt vmcnt(12)
	ds_write_b128 v121, v[184:187] offset:41488
	s_waitcnt vmcnt(11)
	ds_write_b128 v121, v[190:193] offset:9232
	s_waitcnt vmcnt(10)
	ds_write_b128 v121, v[194:197] offset:46096
	s_waitcnt vmcnt(9)
	ds_write_b128 v121, v[198:201] offset:13840
	s_waitcnt vmcnt(8)
	ds_write_b128 v121, v[202:205] offset:50704
	s_waitcnt lgkmcnt(0)
	s_barrier
	ds_read_b128 v[160:163], v124 offset:16
	ds_read_b128 v[164:167], v124 offset:48
	ds_read_b128 v[168:171], v124 offset:4624
	ds_read_b128 v[172:175], v124 offset:4656
	ds_read_b128 v[176:179], v126 offset:36880
	ds_read_b128 v[180:183], v126 offset:36912
	ds_read_b128 v[184:187], v126 offset:41488
	ds_read_b128 v[190:193], v126 offset:41520
	s_waitcnt lgkmcnt(1)
	v_mfma_f32_32x32x16_bf16 v[2:17], v[168:171], v[184:187], v[2:17]
	v_mfma_f32_32x32x16_bf16 v[50:65], v[160:163], v[176:179], v[50:65]
	v_mfma_f32_32x32x16_bf16 v[34:49], v[160:163], v[184:187], v[34:49]
	v_mfma_f32_32x32x16_bf16 v[18:33], v[168:171], v[176:179], v[18:33]
	ds_read_b128 v[160:163], v124 offset:80
	ds_read_b128 v[168:171], v124 offset:4688
	ds_read_b128 v[176:179], v126 offset:36944
	ds_read_b128 v[184:187], v126 offset:41552
	s_waitcnt lgkmcnt(4)
	v_mfma_f32_32x32x16_bf16 v[2:17], v[172:175], v[190:193], v[2:17]
	v_mfma_f32_32x32x16_bf16 v[50:65], v[164:167], v[180:183], v[50:65]
	v_mfma_f32_32x32x16_bf16 v[34:49], v[164:167], v[190:193], v[34:49]
	v_mfma_f32_32x32x16_bf16 v[18:33], v[172:175], v[180:183], v[18:33]
	ds_read_b128 v[164:167], v124 offset:112
	ds_read_b128 v[172:175], v124 offset:4720
	ds_read_b128 v[180:183], v126 offset:36976
	ds_read_b128 v[190:193], v126 offset:41584
	s_waitcnt lgkmcnt(4)
	v_mfma_f32_32x32x16_bf16 v[2:17], v[168:171], v[184:187], v[2:17]
	v_mfma_f32_32x32x16_bf16 v[50:65], v[160:163], v[176:179], v[50:65]
	v_mfma_f32_32x32x16_bf16 v[34:49], v[160:163], v[184:187], v[34:49]
	v_mfma_f32_32x32x16_bf16 v[18:33], v[168:171], v[176:179], v[18:33]
	s_waitcnt lgkmcnt(0)
	v_mfma_f32_32x32x16_bf16 v[2:17], v[172:175], v[190:193], v[2:17]
	v_mfma_f32_32x32x16_bf16 v[50:65], v[164:167], v[180:183], v[50:65]
	v_mfma_f32_32x32x16_bf16 v[34:49], v[164:167], v[190:193], v[34:49]
	v_mfma_f32_32x32x16_bf16 v[18:33], v[172:175], v[180:183], v[18:33]
	s_waitcnt vmcnt(7)
	ds_write_b128 v121, v[140:143] offset:18448
	s_waitcnt vmcnt(6)
	ds_write_b128 v121, v[144:147] offset:55312
	s_waitcnt vmcnt(5)
	ds_write_b128 v121, v[148:151] offset:23056
	s_waitcnt vmcnt(4)
	ds_write_b128 v121, v[108:111] offset:59920
	s_waitcnt vmcnt(3)
	ds_write_b128 v121, v[152:155] offset:27664
	s_waitcnt vmcnt(2)
	ds_write_b128 v121, v[112:115] offset:64528
	s_waitcnt vmcnt(1)
	ds_write_b128 v121, v[156:159] offset:32272
	s_waitcnt vmcnt(0)
	ds_write_b128 v122, v[116:119] offset:32256
	s_waitcnt lgkmcnt(0)
	s_barrier
; #define MFMA(a, b, c) __builtin_amdgcn_mfma_f32_32x32x16_bf16((a), (b), (c), 0, 0, 0)
; template <bool SWAP, class Epi>
; DI void gemm_tile(const u16* __restrict__ A, int lda, const u16* __restrict__ Bt, int ldb, int K, int m0, int n0, char* smem, Epi&& epi) {
;     ...
;   auto compute = [&](int buf) __attribute__((always_inline)) {
;     bf16x8 af[2][2], bfr[2][2];
;     af[0][0] = *(const bf16x8*)(Asb + buf * 128 * 72);
;     af[0][1] = *(const bf16x8*)(Asb + buf * 128 * 72 + 32 * 72);
;     bfr[0][0] = *(const bf16x8*)(Bsb + buf * 128 * 72);
;     bfr[0][1] = *(const bf16x8*)(Bsb + buf * 128 * 72 + 32 * 72);
; #pragma unroll
;     for (int ks = 0; ks < 4; ++ks) {
;       const int c = ks & 1, n = c ^ 1;
;       if (ks < 3) {
;         af[n][0] = *(const bf16x8*)(Asb + buf * 128 * 72 + (ks + 1) * 16);
;         af[n][1] = *(const bf16x8*)(Asb + buf * 128 * 72 + 32 * 72 + (ks + 1) * 16);
;         bfr[n][0] = *(const bf16x8*)(Bsb + buf * 128 * 72 + (ks + 1) * 16);
;         bfr[n][1] = *(const bf16x8*)(Bsb + buf * 128 * 72 + 32 * 72 + (ks + 1) * 16);
;       }
;       __builtin_amdgcn_sched_barrier(0);
; #pragma unroll
;       for (int mi = 0; mi < 2; ++mi)
; #pragma unroll
;         for (int ni = 0; ni < 2; ++ni) {
;           if (SWAP) acc[mi][ni] = MFMA(bfr[c][ni], af[c][mi], acc[mi][ni]);
;           else acc[mi][ni] = MFMA(af[c][mi], bfr[c][ni], acc[mi][ni]);
;         }
;       __builtin_amdgcn_sched_barrier(0);
;     }
;   };
	ds_read_b128 v[108:111], v124 offset:18448
	ds_read_b128 v[112:115], v124 offset:18480
	ds_read_b128 v[116:119], v124 offset:23056
	ds_read_b128 v[140:143], v124 offset:23088
	ds_read_b128 v[144:147], v126 offset:55312
	ds_read_b128 v[148:151], v126 offset:55344
	ds_read_b128 v[152:155], v126 offset:59920
	ds_read_b128 v[156:159], v126 offset:59952
	s_waitcnt lgkmcnt(1)
	v_mfma_f32_32x32x16_bf16 v[2:17], v[116:119], v[152:155], v[2:17]
	v_mfma_f32_32x32x16_bf16 v[50:65], v[108:111], v[144:147], v[50:65]
	v_mfma_f32_32x32x16_bf16 v[34:49], v[108:111], v[152:155], v[34:49]
	v_mfma_f32_32x32x16_bf16 v[18:33], v[116:119], v[144:147], v[18:33]
	ds_read_b128 v[108:111], v124 offset:18512
	ds_read_b128 v[116:119], v124 offset:23120
	ds_read_b128 v[144:147], v126 offset:55376
	ds_read_b128 v[152:155], v126 offset:59984
	s_waitcnt lgkmcnt(4)
	v_mfma_f32_32x32x16_bf16 v[2:17], v[140:143], v[156:159], v[2:17]
	v_mfma_f32_32x32x16_bf16 v[50:65], v[112:115], v[148:151], v[50:65]
	v_mfma_f32_32x32x16_bf16 v[34:49], v[112:115], v[156:159], v[34:49]
	v_mfma_f32_32x32x16_bf16 v[18:33], v[140:143], v[148:151], v[18:33]
	ds_read_b128 v[112:115], v124 offset:18544
	ds_read_b128 v[140:143], v124 offset:23152
	ds_read_b128 v[148:151], v126 offset:55408
	ds_read_b128 v[156:159], v126 offset:60016
	s_waitcnt lgkmcnt(4)
	v_mfma_f32_32x32x16_bf16 v[2:17], v[116:119], v[152:155], v[2:17]
	v_mfma_f32_32x32x16_bf16 v[50:65], v[108:111], v[144:147], v[50:65]
	v_mfma_f32_32x32x16_bf16 v[34:49], v[108:111], v[152:155], v[34:49]
	v_mfma_f32_32x32x16_bf16 v[18:33], v[116:119], v[144:147], v[18:33]
	s_waitcnt lgkmcnt(0)
	v_mfma_f32_32x32x16_bf16 v[2:17], v[140:143], v[156:159], v[2:17]
	v_mfma_f32_32x32x16_bf16 v[50:65], v[112:115], v[148:151], v[50:65]
	v_mfma_f32_32x32x16_bf16 v[34:49], v[112:115], v[156:159], v[34:49]
	v_mfma_f32_32x32x16_bf16 v[18:33], v[140:143], v[148:151], v[18:33]
	s_barrier
; DI unsigned pk2(float a, float b) { f2_t v = {a, b}; bf2_t r = __builtin_convertvector(v, bf2_t); return __builtin_bit_cast(unsigned, r); }
; DI void phase3(const Params& p, char* smem) {
;     ...
;         gemm_tile<false>(P + 3584, INC, (const u16*)(p.ws + WS_WUKVT), 512, 512, tm * 128, tn * 128, smem, [&](f32x16 (&acc)[2][2], int mb, int nb, int r, int hi) __attribute__((always_inline)) {
; #pragma unroll
;           for (int mi = 0; mi < 2; ++mi)
; #pragma unroll
;             for (int g = 0; g < 4; ++g) {
;               const int row0 = mb + mi * 32 + hi * 4 + 8 * g;
;               const float s0 = rs[row0 - tm * 128], s1 = rs[row0 + 1 - tm * 128], s2 = rs[row0 + 2 - tm * 128], s3 = rs[row0 + 3 - tm * 128];
;               const int b = row0 >> 11, t = row0 & (S_ - 1);
; #pragma unroll
;               for (int ni = 0; ni < 2; ++ni) {
;                 const int d = (nb & 127) + ni * 32 + r;
;                 *(uint2*)(VT + ((size_t)((b * 8 + head) * 128 + d)) * S_ + t) = make_uint2(pk2(acc[mi][ni][4 * g] * s0, acc[mi][ni][4 * g + 1] * s1), pk2(acc[mi][ni][4 * g + 2] * s2, acc[mi][ni][4 * g + 3] * s3));
;               }
;             }
;         });
	ds_read_b128 v[148:151], v128
	v_add_u32_e32 v79, s92, v127
	v_or_b32_e32 v66, 8, v79
	v_subrev_u32_e32 v66, s92, v66
	v_lshl_add_u32 v66, v66, 2, s54
	ds_read_b128 v[152:155], v66
	v_or_b32_e32 v66, 16, v79
	v_subrev_u32_e32 v66, s92, v66
	v_lshl_add_u32 v66, v66, 2, s54
	ds_read_b128 v[156:159], v66
	v_or_b32_e32 v66, 24, v79
	v_subrev_u32_e32 v66, s92, v66
	v_lshl_add_u32 v66, v66, 2, s54
	ds_read_b128 v[160:163], v66
	v_or_b32_e32 v66, 32, v79
	v_subrev_u32_e32 v66, s92, v66
	v_lshl_add_u32 v66, v66, 2, s54
	ds_read_b128 v[164:167], v66
	v_or_b32_e32 v66, 40, v79
	v_subrev_u32_e32 v66, s92, v66
	v_lshl_add_u32 v66, v66, 2, s54
	ds_read_b128 v[168:171], v66
	v_or_b32_e32 v66, 48, v79
	v_subrev_u32_e32 v66, s92, v66
	v_lshl_add_u32 v66, v66, 2, s54
	ds_read_b128 v[172:175], v66
	v_or_b32_e32 v66, 56, v79
	v_subrev_u32_e32 v66, s92, v66
	v_lshl_add_u32 v66, v66, 2, s54
	ds_read_b128 v[176:179], v66
	v_lshrrev_b32_e32 v66, 8, v79
	v_and_b32_e32 v66, 56, v66
	v_add_u32_e32 v140, s16, v66
	v_lshl_or_b32 v66, v140, 7, v125
	v_lshlrev_b64 v[140:141], 12, v[66:67]
	v_or_b32_e32 v66, 32, v66
	v_lshlrev_b64 v[142:143], 12, v[66:67]
	v_lshl_add_u64 v[142:143], s[10:11], 0, v[142:143]
	v_lshl_add_u64 v[140:141], s[10:11], 0, v[140:141]
	v_and_b32_e32 v146, 32, v0
	v_cmp_ne_u32_e64 s[96:97], 0, v146
	v_add_co_u32_e32 v144, vcc, -8, v142
	s_nop 1
	v_addc_co_u32_e32 v145, vcc, -1, v143, vcc
	v_cndmask_b32_e64 v144, v140, v144, s[96:97]
	v_cndmask_b32_e64 v145, v141, v145, s[96:97]
	v_mov_b32_e32 v147, 0
	s_waitcnt lgkmcnt(7)
	v_pk_mul_f32 v[50:51], v[50:51], v[148:149]
	v_pk_mul_f32 v[52:53], v[52:53], v[150:151]
	v_pk_mul_f32 v[34:35], v[34:35], v[148:149]
	v_pk_mul_f32 v[36:37], v[36:37], v[150:151]
	v_and_b32_e32 v146, 0x7c4, v79
	v_lshlrev_b32_e32 v146, 1, v146
	v_cvt_pk_bf16_f32 v180, v50, v51
	v_cvt_pk_bf16_f32 v181, v52, v53
	v_cvt_pk_bf16_f32 v182, v34, v35
	v_cvt_pk_bf16_f32 v183, v36, v37
	v_lshl_add_u64 v[190:191], v[144:145], 0, v[146:147]
	s_nop 0
	v_permlane32_swap_b32_e32 v180, v182
	v_permlane32_swap_b32_e32 v181, v183
	global_store_dwordx4 v[190:191], v[180:183], off
	s_waitcnt lgkmcnt(6)
	v_pk_mul_f32 v[54:55], v[54:55], v[152:153]
	v_pk_mul_f32 v[56:57], v[56:57], v[154:155]
	v_pk_mul_f32 v[38:39], v[38:39], v[152:153]
	v_pk_mul_f32 v[40:41], v[40:41], v[154:155]
	v_bitop3_b32 v146, v79, s84, 8 bitop3:0xc8
	v_lshlrev_b32_e32 v146, 1, v146
	v_cvt_pk_bf16_f32 v184, v54, v55
	v_cvt_pk_bf16_f32 v185, v56, v57
	v_cvt_pk_bf16_f32 v186, v38, v39
	v_cvt_pk_bf16_f32 v187, v40, v41
	v_lshl_add_u64 v[192:193], v[144:145], 0, v[146:147]
	s_nop 0
	v_permlane32_swap_b32_e32 v184, v186
	v_permlane32_swap_b32_e32 v185, v187
	global_store_dwordx4 v[192:193], v[184:187], off
	s_waitcnt lgkmcnt(5)
	v_pk_mul_f32 v[58:59], v[58:59], v[156:157]
	v_pk_mul_f32 v[60:61], v[60:61], v[158:159]
	v_pk_mul_f32 v[42:43], v[42:43], v[156:157]
	v_pk_mul_f32 v[44:45], v[44:45], v[158:159]
	v_bitop3_b32 v146, v79, s85, 16 bitop3:0xc8
	v_lshlrev_b32_e32 v146, 1, v146
	v_cvt_pk_bf16_f32 v180, v58, v59
	v_cvt_pk_bf16_f32 v181, v60, v61
	v_cvt_pk_bf16_f32 v182, v42, v43
	v_cvt_pk_bf16_f32 v183, v44, v45
	v_lshl_add_u64 v[190:191], v[144:145], 0, v[146:147]
	s_nop 0
	v_permlane32_swap_b32_e32 v180, v182
	v_permlane32_swap_b32_e32 v181, v183
	global_store_dwordx4 v[190:191], v[180:183], off
	s_waitcnt lgkmcnt(4)
	v_pk_mul_f32 v[62:63], v[62:63], v[160:161]
	v_pk_mul_f32 v[64:65], v[64:65], v[162:163]
	v_pk_mul_f32 v[46:47], v[46:47], v[160:161]
	v_pk_mul_f32 v[48:49], v[48:49], v[162:163]
	v_bitop3_b32 v146, v79, s86, 24 bitop3:0xc8
	v_lshlrev_b32_e32 v146, 1, v146
	v_cvt_pk_bf16_f32 v184, v62, v63
	v_cvt_pk_bf16_f32 v185, v64, v65
	v_cvt_pk_bf16_f32 v186, v46, v47
	v_cvt_pk_bf16_f32 v187, v48, v49
	v_lshl_add_u64 v[192:193], v[144:145], 0, v[146:147]
	s_nop 0
	v_permlane32_swap_b32_e32 v184, v186
	v_permlane32_swap_b32_e32 v185, v187
	global_store_dwordx4 v[192:193], v[184:187], off
	s_waitcnt lgkmcnt(3)
	v_pk_mul_f32 v[18:19], v[18:19], v[164:165]
	v_pk_mul_f32 v[20:21], v[20:21], v[166:167]
	v_pk_mul_f32 v[2:3], v[2:3], v[164:165]
	v_pk_mul_f32 v[4:5], v[4:5], v[166:167]
	v_bitop3_b32 v146, v79, s87, 32 bitop3:0xc8
	v_lshlrev_b32_e32 v146, 1, v146
	v_cvt_pk_bf16_f32 v180, v18, v19
	v_cvt_pk_bf16_f32 v181, v20, v21
	v_cvt_pk_bf16_f32 v182, v2, v3
	v_cvt_pk_bf16_f32 v183, v4, v5
	v_lshl_add_u64 v[190:191], v[144:145], 0, v[146:147]
	s_nop 0
	v_permlane32_swap_b32_e32 v180, v182
	v_permlane32_swap_b32_e32 v181, v183
	global_store_dwordx4 v[190:191], v[180:183], off
	s_waitcnt lgkmcnt(2)
	v_pk_mul_f32 v[22:23], v[22:23], v[168:169]
	v_pk_mul_f32 v[24:25], v[24:25], v[170:171]
	v_pk_mul_f32 v[6:7], v[6:7], v[168:169]
	v_pk_mul_f32 v[8:9], v[8:9], v[170:171]
	v_bitop3_b32 v146, v79, s88, 40 bitop3:0xc8
	v_lshlrev_b32_e32 v146, 1, v146
	v_cvt_pk_bf16_f32 v184, v22, v23
	v_cvt_pk_bf16_f32 v185, v24, v25
	v_cvt_pk_bf16_f32 v186, v6, v7
	v_cvt_pk_bf16_f32 v187, v8, v9
	v_lshl_add_u64 v[192:193], v[144:145], 0, v[146:147]
	s_nop 0
	v_permlane32_swap_b32_e32 v184, v186
	v_permlane32_swap_b32_e32 v185, v187
	global_store_dwordx4 v[192:193], v[184:187], off
	s_waitcnt lgkmcnt(1)
	v_pk_mul_f32 v[26:27], v[26:27], v[172:173]
	v_pk_mul_f32 v[28:29], v[28:29], v[174:175]
	v_pk_mul_f32 v[10:11], v[10:11], v[172:173]
	v_pk_mul_f32 v[12:13], v[12:13], v[174:175]
	v_bitop3_b32 v146, v79, s89, 48 bitop3:0xc8
	v_lshlrev_b32_e32 v146, 1, v146
	v_cvt_pk_bf16_f32 v180, v26, v27
	v_cvt_pk_bf16_f32 v181, v28, v29
	v_cvt_pk_bf16_f32 v182, v10, v11
	v_cvt_pk_bf16_f32 v183, v12, v13
	v_lshl_add_u64 v[190:191], v[144:145], 0, v[146:147]
	s_nop 0
	v_permlane32_swap_b32_e32 v180, v182
	v_permlane32_swap_b32_e32 v181, v183
	global_store_dwordx4 v[190:191], v[180:183], off
	s_waitcnt lgkmcnt(0)
	v_pk_mul_f32 v[30:31], v[30:31], v[176:177]
	v_pk_mul_f32 v[32:33], v[32:33], v[178:179]
	v_pk_mul_f32 v[14:15], v[14:15], v[176:177]
	v_pk_mul_f32 v[16:17], v[16:17], v[178:179]
	v_bitop3_b32 v146, v79, s90, 56 bitop3:0xc8
	v_lshlrev_b32_e32 v146, 1, v146
	v_cvt_pk_bf16_f32 v184, v30, v31
	v_cvt_pk_bf16_f32 v185, v32, v33
	v_cvt_pk_bf16_f32 v186, v14, v15
	v_cvt_pk_bf16_f32 v187, v16, v17
	v_lshl_add_u64 v[192:193], v[144:145], 0, v[146:147]
	s_nop 0
	v_permlane32_swap_b32_e32 v184, v186
	v_permlane32_swap_b32_e32 v185, v187
	global_store_dwordx4 v[192:193], v[184:187], off
	s_branch .Lp3_next
